# static s_setprio 1 for waves 4-7 inside the dense attention loops; no store drain before the next attention unit's first loads
# baseline (speedup 1.0000x reference)
.LBB0_155:
	s_andn2_b64 vcc, exec, s[38:39]
	s_mov_b64 s[10:11], -1
	s_cbranch_vccnz .LBB0_146
	s_cmpk_gt_i32 s52, 0x3ff
	s_mov_b64 s[38:39], -1
	s_cbranch_scc0 .LBB0_172
	s_lshl_b32 s0, s52, 4
	s_and_b32 s11, s52, 15
	s_and_b32 s10, s0, 0xffffff00
	s_addk_i32 s10, 0xc000
	s_lshl_b32 s38, s11, 6
	s_mov_b64 s[40:41], -1
	s_and_b64 vcc, exec, s[60:61]
	s_cbranch_vccz .LBB0_168
	v_mov_b32_e32 v3, v249
	s_andn2_b64 vcc, exec, s[22:23]
	v_readfirstlane_b32 s0, v3
	s_ashr_i32 s0, s0, 1
	s_andn2_b32 s0, s0, 31
	v_and_b32_e32 v4, 31, v3
	s_add_i32 s0, s0, s10
	v_or_b32_e32 v0, s0, v4
	v_mad_i64_i32 v[6:7], s[24:25], s4, v0, 0
	v_bfe_u32 v96, v3, 5, 1
	v_lshl_add_u64 v[6:7], v[6:7], 1, s[74:75]
	s_lshl_b32 s0, s38, 1
	v_lshl_add_u64 v[102:103], v[6:7], 0, s[0:1]
	v_lshlrev_b32_e32 v0, 4, v96
	v_lshl_add_u64 v[90:91], v[102:103], 0, v[0:1]
	global_load_dwordx4 v[78:81], v[90:91], off
	global_load_dwordx4 v[74:77], v[90:91], off offset:32
	global_load_dwordx4 v[70:73], v[90:91], off offset:64
	global_load_dwordx4 v[66:69], v[90:91], off offset:96
	s_cbranch_vccnz .LBB0_160
	s_lshl_b32 s0, s11, 2
	v_mov_b32_e32 v0, s0
	global_load_dword v0, v0, s[56:57]
	v_cmp_eq_u32_e32 vcc, 0, v96
	s_waitcnt vmcnt(0)
	v_mul_f32_e32 v2, 0x3fb8aa3b, v0
	v_cndmask_b32_e64 v82, 0, 1.0, vcc
	s_branch .LBB0_161

.LBB0_264:
	s_and_b64 vcc, exec, s[38:39]
	s_cbranch_vccz .LBB0_145
	v_mov_b32_e32 v3, v249
	s_bfe_u32 s24, s52, 0x20001
	v_readfirstlane_b32 s0, v3
	s_and_b32 s25, s52, 1
	s_ashr_i32 s26, s0, 5
	s_lshl_b32 s3, s25, 4
	s_and_b32 s0, s26, -2
	s_lshl_b32 s72, s24, 4
	v_and_b32_e32 v82, 15, v3
	s_lshl_b32 s27, s53, 11
	s_add_i32 s3, s0, s3
	v_bfe_u32 v59, v3, 4, 1
	v_or_b32_e32 v107, s72, v82
	s_add_i32 s0, s27, 0x2000
	v_or_b32_e32 v96, s3, v59
	v_or_b32_e32 v0, s0, v107
	v_lshl_add_u32 v0, v96, 6, v0
	v_mad_i64_i32 v[6:7], s[10:11], s4, v0, 0
	v_bfe_u32 v4, v3, 5, 1
	v_lshl_add_u64 v[6:7], v[6:7], 1, s[74:75]
	s_lshl_b32 s0, s54, 7
	v_lshl_add_u64 v[102:103], v[6:7], 0, s[0:1]
	v_lshlrev_b32_e32 v0, 4, v4
	v_lshl_add_u64 v[90:91], v[102:103], 0, v[0:1]
	global_load_dwordx4 v[78:81], v[90:91], off
	global_load_dwordx4 v[74:77], v[90:91], off offset:32
	global_load_dwordx4 v[70:73], v[90:91], off offset:64
	global_load_dwordx4 v[66:69], v[90:91], off offset:96
	s_cmp_lt_i32 s24, 1
	s_cbranch_scc1 .LBB0_270
	s_cmp_eq_u32 s24, 1
	s_mov_b64 s[10:11], -1
	s_cbranch_scc1 .LBB0_268
	s_cmp_eq_u32 s24, 2
	s_cselect_b32 s24, 24, 32
	s_mov_b64 s[10:11], 0

.Lam96_pre:
	v_readfirstlane_b32 s26, v249
	s_nop 3
	s_cmp_lt_u32 s26, 0x100
	s_cbranch_scc1 .Lam96_noprio
	s_setprio 1

.Lam96_nos2:
	s_waitcnt vmcnt(0)
	ds_write_b128 v140, v[98:101] offset:12288
	s_add_i32 s25, s25, 1
	s_waitcnt lgkmcnt(0)
	s_barrier
	s_cmp_lg_u32 s25, 40
	s_cbranch_scc1 .Lam96_top
	s_mov_b32 s2, 0x41000000
	s_setprio 0
	s_branch .LBB0_333

.LBB0_338:
	s_lshl_b32 s3, s52, 8
	v_mov_b32_e32 v3, v249
	s_lshl_b32 s11, s53, 11
	s_and_b32 s3, s3, 0x700
	s_or_b32 s3, s11, s3
	v_readfirstlane_b32 s0, v3
	v_and_b32_e32 v4, 31, v3
	s_addk_i32 s3, 0x2000
	s_ashr_i32 s0, s0, 1
	s_andn2_b32 s0, s0, 31
	v_or_b32_e32 v0, s3, v4
	v_add_u32_e32 v0, s0, v0
	v_mad_i64_i32 v[6:7], s[24:25], s4, v0, 0
	v_bfe_u32 v54, v3, 5, 1
	v_lshl_add_u64 v[6:7], v[6:7], 1, s[74:75]
	s_lshl_b32 s0, s44, 1
	v_lshl_add_u64 v[102:103], v[6:7], 0, s[0:1]
	v_lshlrev_b32_e32 v0, 4, v54
	v_lshl_add_u64 v[90:91], v[102:103], 0, v[0:1]
	global_load_dwordx4 v[78:81], v[90:91], off
	global_load_dwordx4 v[74:77], v[90:91], off offset:32
	global_load_dwordx4 v[70:73], v[90:91], off offset:64
	global_load_dwordx4 v[66:69], v[90:91], off offset:96
	s_and_b64 vcc, exec, s[38:39]
	s_cbranch_vccnz .LBB0_340
	s_lshl_b32 s0, s54, 2
	v_mov_b32_e32 v0, s0
	global_load_dword v0, v0, s[56:57]
	v_cmp_eq_u32_e32 vcc, 0, v54
	s_waitcnt vmcnt(0)
	v_mul_f32_e32 v2, 0x3fb8aa3b, v0
	v_cndmask_b32_e64 v55, 0, 1.0, vcc
	s_branch .LBB0_341

.Lad64_exp:
	v_exp_f32_e32 v34, v34
	v_exp_f32_e32 v35, v35
	v_exp_f32_e32 v36, v36
	v_exp_f32_e32 v37, v37
	v_exp_f32_e32 v38, v38
	v_exp_f32_e32 v39, v39
	v_exp_f32_e32 v40, v40
	v_exp_f32_e32 v41, v41
	v_cvt_pk_bf16_f32 v220, v34, v35
	v_cvt_pk_bf16_f32 v221, v36, v37
	v_cvt_pk_bf16_f32 v222, v38, v39
	v_cvt_pk_bf16_f32 v223, v40, v41
	v_add_f32_e32 v208, v34, v35
	v_add_f32_e32 v209, v36, v37
	v_add_f32_e32 v208, v208, v38
	v_add_f32_e32 v209, v209, v39
	v_add_f32_e32 v208, v208, v40
	v_add_f32_e32 v209, v209, v41
	v_add_f32_e32 v96, v96, v208
	v_add_f32_e32 v96, v96, v209
	s_waitcnt lgkmcnt(10)
	v_mfma_f32_32x32x16_bf16 v[18:33], v[180:183], v[220:223], v[18:33]
	s_waitcnt lgkmcnt(8)
	v_mfma_f32_32x32x16_bf16 v[2:17], v[184:187], v[220:223], v[2:17]
	ds_read_b64_tr_b16 v[204:205], v134 offset:14336
	ds_read_b64_tr_b16 v[206:207], v134 offset:15360
	ds_read_b64_tr_b16 v[216:217], v117 offset:14336
	ds_read_b64_tr_b16 v[218:219], v117 offset:15360
	v_exp_f32_e32 v42, v42
	v_exp_f32_e32 v43, v43
	v_exp_f32_e32 v44, v44
	v_exp_f32_e32 v45, v45
	v_exp_f32_e32 v46, v46
	v_exp_f32_e32 v47, v47
	v_exp_f32_e32 v48, v48
	v_exp_f32_e32 v49, v49
	v_cvt_pk_bf16_f32 v224, v42, v43
	v_cvt_pk_bf16_f32 v225, v44, v45
	v_cvt_pk_bf16_f32 v226, v46, v47
	v_cvt_pk_bf16_f32 v227, v48, v49
	v_add_f32_e32 v208, v42, v43
	v_add_f32_e32 v209, v44, v45
	v_add_f32_e32 v208, v208, v46
	v_add_f32_e32 v209, v209, v47
	v_add_f32_e32 v208, v208, v48
	v_add_f32_e32 v209, v209, v49
	v_add_f32_e32 v96, v96, v208
	v_add_f32_e32 v96, v96, v209
	s_waitcnt lgkmcnt(10)
	v_mfma_f32_32x32x16_bf16 v[18:33], v[188:191], v[224:227], v[18:33]
	s_waitcnt lgkmcnt(8)
	v_mfma_f32_32x32x16_bf16 v[2:17], v[192:195], v[224:227], v[2:17]
	v_exp_f32_e32 v50, v50
	v_exp_f32_e32 v51, v51
	v_exp_f32_e32 v52, v52
	v_exp_f32_e32 v53, v53
	v_exp_f32_e32 v54, v54
	v_exp_f32_e32 v55, v55
	v_exp_f32_e32 v56, v56
	v_exp_f32_e32 v57, v57
	v_cvt_pk_bf16_f32 v228, v50, v51
	v_cvt_pk_bf16_f32 v229, v52, v53
	v_cvt_pk_bf16_f32 v230, v54, v55
	v_cvt_pk_bf16_f32 v231, v56, v57
	v_add_f32_e32 v208, v50, v51
	v_add_f32_e32 v209, v52, v53
	v_add_f32_e32 v208, v208, v54
	v_add_f32_e32 v209, v209, v55
	v_add_f32_e32 v208, v208, v56
	v_add_f32_e32 v209, v209, v57
	v_add_f32_e32 v96, v96, v208
	v_add_f32_e32 v96, v96, v209
	s_waitcnt lgkmcnt(6)
	v_mfma_f32_32x32x16_bf16 v[18:33], v[196:199], v[228:231], v[18:33]
	s_waitcnt lgkmcnt(4)
	v_mfma_f32_32x32x16_bf16 v[2:17], v[200:203], v[228:231], v[2:17]
	v_exp_f32_e32 v58, v58
	v_exp_f32_e32 v59, v59
	v_exp_f32_e32 v60, v60
	v_exp_f32_e32 v61, v61
	v_exp_f32_e32 v62, v62
	v_exp_f32_e32 v63, v63
	v_exp_f32_e32 v64, v64
	v_exp_f32_e32 v65, v65
	v_cvt_pk_bf16_f32 v232, v58, v59
	v_cvt_pk_bf16_f32 v233, v60, v61
	v_cvt_pk_bf16_f32 v234, v62, v63
	v_cvt_pk_bf16_f32 v235, v64, v65
	v_add_f32_e32 v208, v58, v59
	v_add_f32_e32 v209, v60, v61
	v_add_f32_e32 v208, v208, v62
	v_add_f32_e32 v209, v209, v63
	v_add_f32_e32 v208, v208, v64
	v_add_f32_e32 v209, v209, v65
	v_add_f32_e32 v96, v96, v208
	v_add_f32_e32 v96, v96, v209
	s_waitcnt lgkmcnt(2)
	v_mfma_f32_32x32x16_bf16 v[18:33], v[204:207], v[232:235], v[18:33]
	s_waitcnt lgkmcnt(0)
	v_mfma_f32_32x32x16_bf16 v[2:17], v[216:219], v[232:235], v[2:17]
	s_and_b32 s26, s24, 0x4000
	v_add3_u32 v134, s26, v106, v101
	v_add3_u32 v117, s26, v97, v99
	s_waitcnt vmcnt(1)
	ds_write_b128 v134, v[82:85]
	s_waitcnt vmcnt(0)
	ds_write_b128 v117, v[86:89] offset:8192
	s_add_i32 s10, s10, 1
	s_addk_i32 s24, 0x4000
	s_waitcnt lgkmcnt(0)
	s_barrier
	s_cmp_lg_u32 s10, 39
	s_cbranch_scc1 .Lad64_top
	s_setprio 0
	s_branch .LBB0_345
